# as the unstaggered MLA loop rewrite, and phase 3 runs every wave at priority 0 (no static priority for waves 4-7)
# speedup vs baseline: 1.0067x; 1.0067x over previous
.LBB0_717:
	s_cmp_lt_i32 s22, 4
	s_cselect_b64 s[0:1], -1, 0
	s_cmp_gt_i32 s23, 3
	s_cselect_b64 s[2:3], -1, 0
	s_and_b64 s[0:1], s[0:1], s[2:3]
	s_andn2_b64 vcc, exec, s[0:1]
	s_cbranch_vccnz .LBB0_952
	s_movk_i32 s0, 0xff
	v_cmp_lt_u32_e32 vcc, s0, v208
	s_and_saveexec_b64 s[0:1], vcc
	s_setprio 0
	s_or_b64 exec, exec, s[0:1]
	s_cmpk_eq_i32 s82, 0x100
	s_cselect_b64 s[0:1], -1, 0
	v_writelane_b32 v247, s0, 41
	s_movk_i32 s2, 0x800
	v_and_b32_e32 v1, 7, v208
	v_writelane_b32 v247, s1, 42
	s_and_b64 s[0:1], s[0:1], exec
	s_cselect_b32 s88, s2, 0x810
	s_cmp_ge_i32 s96, s88
	s_cbranch_scc1 .LBB0_856
	v_and_b32_e32 v15, 31, v208
	v_bfe_u32 v3, v208, 5, 1
	s_movk_i32 s0, 0x80
	v_min_u32_e32 v141, 15, v15
	v_cmp_gt_u32_e32 vcc, s0, v208
	s_movk_i32 s0, 0x100
	v_lshlrev_b32_e32 v212, 2, v3
	v_lshlrev_b32_e32 v14, 3, v3
	v_lshrrev_b32_e32 v147, 3, v208
	v_cmp_gt_u32_e64 s[2:3], s0, v208
	s_movk_i32 s0, 0xd0
	v_lshrrev_b32_e32 v12, 2, v208
	v_cmp_eq_u32_e64 s[6:7], 0, v3
	v_lshlrev_b32_e32 v144, 4, v3
	v_sub_u32_e32 v3, v141, v212
	v_mad_u32_u24 v199, v147, s0, 0
	v_mad_u32_u24 v201, v12, s0, 0
	v_mad_u32_u24 v213, v15, s0, 0
	v_cmp_gt_i32_e64 s[0:1], 0, v3
	v_min_u32_e32 v8, 16, v15
	v_mul_u32_u24_e32 v16, 0x600, v141
	v_writelane_b32 v247, s0, 22
	v_mov_b32_e32 v17, 0
	v_lshlrev_b32_e32 v2, 9, v147
	v_writelane_b32 v247, s1, 23
	v_cmp_gt_i32_e64 s[0:1], 1, v3
	v_mov_b32_e32 v4, 0x1e00
	v_cndmask_b32_e32 v10, v4, v2, vcc
	v_writelane_b32 v247, s0, 24
	v_min_u32_e32 v2, 63, v208
	v_mov_b32_e32 v145, v17
	v_writelane_b32 v247, s1, 25
	v_cmp_gt_i32_e64 s[0:1], 2, v3
	v_lshrrev_b32_e32 v2, 2, v2
	v_mul_u32_u24_e32 v11, 0xc00, v2
	v_writelane_b32 v247, s0, 26
	v_lshlrev_b32_e32 v2, 3, v208
	v_lshlrev_b32_e32 v142, 4, v1
	v_writelane_b32 v247, s1, 27
	v_cmp_gt_i32_e64 s[0:1], 3, v3
	v_mov_b32_e32 v143, v17
	v_and_b32_e32 v2, 24, v2
	v_writelane_b32 v247, s0, 28
	v_lshlrev_b32_e32 v4, 4, v208
	v_and_b32_e32 v202, 48, v4
	v_writelane_b32 v247, s1, 29
	v_cmp_gt_i32_e64 s[0:1], 8, v3
	v_lshlrev_b32_e32 v4, 6, v147
	v_sub_u32_e32 v204, v199, v4
	v_writelane_b32 v247, s0, 16
	v_mul_u32_u24_e32 v4, 0x1800, v141
	v_mov_b32_e32 v5, v17
	v_writelane_b32 v247, s1, 17
	v_cmp_gt_i32_e64 s[0:1], 9, v3
	v_mul_u32_u24_e32 v6, 0x1800, v147
	v_mov_b32_e32 v7, 0x16800
	v_writelane_b32 v247, s0, 43
	v_cndmask_b32_e32 v6, v7, v6, vcc
	v_mov_b32_e32 v7, v17
	v_writelane_b32 v247, s1, 44
	v_cmp_gt_i32_e64 s[0:1], 10, v3
	v_mul_u32_u24_e32 v150, 0x1800, v12
	v_lshlrev_b32_e32 v148, 10, v147
	v_writelane_b32 v247, s0, 45
	v_lshlrev_b32_e32 v140, 3, v1
	s_movk_i32 s8, 0x90
	v_writelane_b32 v247, s1, 46
	v_cmp_gt_i32_e64 s[0:1], 11, v3
	v_and_b32_e32 v3, 63, v208
	v_cmp_gt_u32_e64 s[26:27], 32, v3
	v_writelane_b32 v247, s0, 47
	v_cmp_eq_u32_e64 s[28:29], 0, v3
	v_sub_u32_e32 v3, v8, v212
	v_writelane_b32 v247, s1, 48
	v_cmp_lt_u32_e64 s[0:1], 15, v15
	v_lshl_add_u64 v[8:9], s[20:21], 0, v[16:17]
	v_lshl_add_u64 v[8:9], v[8:9], 0, v[144:145]
	v_writelane_b32 v247, s0, 18
	v_lshlrev_b32_e32 v16, 1, v10
	v_and_b32_e32 v205, 0x60, v142
	v_writelane_b32 v247, s1, 19
	v_cmp_lt_i32_e64 s[0:1], 0, v3
	v_cmp_gt_u32_e64 s[4:5], 2, v1
	v_mul_u32_u24_e32 v198, 0xd0, v147
	v_writelane_b32 v247, s0, 49
	s_mov_b32 s9, 0
	v_mul_u32_u24_e32 v200, 0xd0, v12
	v_writelane_b32 v247, s1, 50
	v_cmp_lt_i32_e64 s[0:1], 1, v3
	v_mul_u32_u24_e32 v203, 0x90, v147
	v_add_u32_e32 v206, v204, v205
	v_writelane_b32 v247, s0, 51
	v_and_b32_e32 v207, 8, v140
	v_mul_u32_u24_e32 v210, 0x90, v15
	v_writelane_b32 v247, s1, 52
	v_cmp_lt_i32_e64 s[0:1], 2, v3
	v_mul_u32_u24_e32 v211, 0xd0, v15
	v_add_u32_e32 v214, 0, v144
	v_writelane_b32 v247, s0, 53
	s_movk_i32 s45, 0x1800
	v_lshlrev_b32_e32 v146, 15, v147
	v_writelane_b32 v247, s1, 54
	v_cmp_lt_i32_e64 s[0:1], 3, v3
	v_add_u32_e32 v215, 1, v15
	v_not_b32_e32 v216, v212
	v_writelane_b32 v247, s0, 55
	v_mov_b32_e32 v149, v17
	s_waitcnt lgkmcnt(0)
	v_mov_b32_e32 v151, v17
	v_writelane_b32 v247, s1, 56
	v_cmp_lt_i32_e64 s[0:1], 8, v3
	v_cndmask_b32_e32 v217, 15, v147, vcc
	s_mov_b32 s86, 0xf149f2ca
	v_writelane_b32 v247, s0, 57
	s_mov_b32 s87, 0xc2c80000
	s_mov_b32 s46, 0x43180000
	v_writelane_b32 v247, s1, 58
	v_cmp_lt_i32_e64 s[0:1], 9, v3
	v_lshlrev_b32_e32 v176, 1, v2
	s_mov_b32 s47, 0x41000000
	v_writelane_b32 v247, s0, 59
	v_bfrev_b32_e32 v50, 1
	v_mov_b32_e32 v218, 0xf149f2ca
	v_writelane_b32 v247, s1, 60
	v_cmp_lt_i32_e64 s[0:1], 10, v3
	v_mov_b32_e32 v219, 0x42c80000
	v_mov_b32_e32 v220, 0x7149f2ca
	v_writelane_b32 v247, s0, 61
	v_mov_b32_e32 v221, 0xc00000
	s_mov_b32 s33, s96
	v_writelane_b32 v247, s1, 62
	v_cmp_lt_i32_e64 s[0:1], 11, v3
	v_sub_u32_e32 v3, v15, v212
	v_cmp_lt_i32_e64 s[90:91], 1, v3
	v_writelane_b32 v247, s0, 63
	v_cmp_lt_i32_e64 s[52:53], 2, v3
	v_cmp_lt_i32_e64 s[54:55], 3, v3
	v_writelane_b32 v246, s1, 0
	v_cmp_lt_i32_e64 s[0:1], 0, v3
	v_cmp_lt_i32_e64 s[56:57], 8, v3
	v_cmp_lt_i32_e64 s[58:59], 9, v3
	v_writelane_b32 v247, s0, 39
	v_cmp_lt_i32_e64 s[60:61], 10, v3
	v_cmp_lt_i32_e64 s[62:63], 11, v3
	v_writelane_b32 v247, s1, 40
	s_mov_b64 s[0:1], 0x1a00c800
	v_lshl_add_u64 v[152:153], v[8:9], 0, s[0:1]
	v_lshl_add_u64 v[8:9], s[20:21], 0, v[16:17]
	v_lshl_add_u64 v[8:9], v[8:9], 0, v[142:143]
	s_mov_b64 s[0:1], 0x1a012800
	v_lshlrev_b32_e32 v16, 1, v11
	v_lshl_add_u64 v[154:155], v[8:9], 0, s[0:1]
	v_lshl_add_u64 v[8:9], s[20:21], 0, v[16:17]
	v_lshlrev_b32_e32 v16, 1, v2
	v_lshl_add_u64 v[8:9], v[8:9], 0, v[16:17]
	s_mov_b64 s[0:1], 0x19ff1b00
	v_lshlrev_b32_e32 v16, 5, v147
	v_lshl_add_u64 v[156:157], v[8:9], 0, s[0:1]
	v_lshl_add_u64 v[8:9], s[20:21], 0, v[16:17]
	v_lshl_add_u64 v[8:9], v[8:9], 0, v[142:143]
	s_mov_b64 s[0:1], 0x1a016800
	v_lshl_add_u64 v[158:159], v[8:9], 0, s[0:1]
	s_add_u32 s0, s20, 0x19ff0800
	s_addc_u32 s1, s21, 0
	s_add_u32 s14, s20, 0x19ff0c00
	s_addc_u32 s15, s21, 0
	v_writelane_b32 v246, s0, 1
	v_cmp_lt_i32_e64 s[64:65], 16, v3
	v_cmp_lt_i32_e64 s[66:67], 17, v3
	v_writelane_b32 v246, s1, 2
	v_lshl_add_u64 v[4:5], s[0:1], 0, v[4:5]
	s_add_u32 s0, s20, 0x1a008800
	s_addc_u32 s1, s21, 0
	s_add_u32 s10, s20, 0x19fe8800
	s_addc_u32 s11, s21, 0
	s_add_u32 s92, s20, 0x4f60000
	v_writelane_b32 v246, s10, 3
	s_addc_u32 s93, s21, 0
	v_lshl_add_u64 v[160:161], v[4:5], 0, v[144:145]
	v_writelane_b32 v246, s11, 4
	s_add_u32 s10, s20, 0x15f60000
	v_writelane_b32 v247, s10, 20
	s_addc_u32 s10, s21, 0
	v_writelane_b32 v247, s10, 21
	s_add_u32 s10, s20, 0x17f60000
	v_writelane_b32 v247, s10, 30
	s_addc_u32 s10, s21, 0
	v_writelane_b32 v247, s10, 31
	s_add_u32 s10, s20, 0x12f60000
	s_addc_u32 s11, s21, 0
	v_writelane_b32 v247, s10, 32
	v_lshl_add_u64 v[4:5], s[14:15], 0, v[6:7]
	v_lshl_add_u64 v[162:163], v[4:5], 0, v[142:143]
	v_writelane_b32 v247, s11, 33
	s_add_u32 s10, s20, 0x10f60000
	v_lshl_add_u64 v[4:5], s[0:1], 0, v[16:17]
	v_writelane_b32 v247, s10, 34
	s_addc_u32 s10, s21, 0
	v_lshl_add_u64 v[164:165], v[4:5], 0, v[142:143]
	v_lshl_add_u64 v[4:5], s[0:1], 0, v[142:143]
	s_add_u32 s0, s20, 0xf60000
	v_writelane_b32 v247, s10, 35
	v_lshl_add_u64 v[166:167], v[4:5], 0, v[16:17]
	s_addc_u32 s1, s21, 0
	v_and_b32_e32 v4, 3, v208
	v_writelane_b32 v247, s0, 37
	v_mul_hi_u32_u24_e32 v5, 0x1800, v12
	v_lshl_or_b32 v4, v4, 4, v150
	v_writelane_b32 v247, s1, 38
	v_lshl_add_u64 v[4:5], s[20:21], 0, v[4:5]
	s_mov_b64 s[0:1], 0x4fc1300
	v_lshl_or_b32 v16, v147, 16, v142
	v_lshl_add_u64 v[168:169], v[4:5], 0, s[0:1]
	v_lshl_add_u64 v[4:5], s[20:21], 0, v[16:17]
	s_mov_b64 s[0:1], 0x17f60080
	v_or_b32_e32 v16, v148, v142
	v_lshl_add_u64 v[170:171], v[4:5], 0, s[0:1]
	v_lshl_add_u64 v[6:7], s[20:21], 0, v[16:17]
	s_mov_b64 s[0:1], 0x15f70000
	v_lshl_add_u64 v[172:173], v[6:7], 0, s[0:1]
	s_mov_b64 s[0:1], 0x10f60100
	v_mad_u32_u24 v143, v147, s8, 0
	s_lshl_b32 s84, s96, 7
	s_lshl_b32 s85, s82, 7
	v_lshl_add_u64 v[174:175], v[4:5], 0, s[0:1]
	v_or_b32_e32 v145, 0x80, v147
	v_cmp_lt_i32_e64 s[68:69], 18, v3
	v_cmp_lt_i32_e64 s[70:71], 19, v3
	v_cmp_lt_i32_e64 s[72:73], 24, v3
	v_cmp_lt_i32_e64 s[74:75], 25, v3
	v_cmp_lt_i32_e64 s[76:77], 26, v3
	v_cmp_lt_i32_e64 s[78:79], 27, v3
	s_branch .LBB0_723
